# pvprio + score-minus-max subs packed (v_pk_add neg, fresh registers) in 10 more attention blocks (NA copies A/C, SWA passes): -40 VALU static
# speedup vs baseline: 1.0076x; 1.0040x over previous
; template <int MODE> ...
;     ...
;             bf16x8 kf[2][2][2];
; #pragma unroll
;             for (int jj = 0; jj < 2; ++jj)
; #pragma unroll
;                 for (int kt = 0; kt < 2; ++kt)
; #pragma unroll
;                     for (int ks = 0; ks < 2; ++ks) kf[jj][kt][ks] = *(const LAS bf16x8*)(Sl + kad[jj][ks] + (32 * hf + 16 * kt) * 128);
;             f32x4 bb[2][2];
; #pragma unroll
;             for (int jj = 0; jj < 2; ++jj) { const LAS f32x4* bl = bcp + ((MODE == 0) ? (dr0 + t - act0) * 8 : 16 * t + 8 * hf) + bofs[jj];
; #pragma unroll
;                 for (int kt = 0; kt < 2; ++kt) bb[jj][kt] = bl[4 * kt]; }
;             s16x4 vlo[2][4], vhi[2][4];
; #pragma unroll
;             for (int jj = 0; jj < 2; ++jj)
; #pragma unroll
;                 for (int dt = 0; dt < 4; ++dt) { const LAS unsigned char* vp = Sl + vad[jj] + (32 * hf) * 128 + ((dt ^ sv) << 5);
;                     vlo[jj][dt] = __builtin_bit_cast(s16x4, __builtin_amdgcn_ds_read_tr16_b64_v4i16((LAS s16x4*)(vp)));
;                     vhi[jj][dt] = __builtin_bit_cast(s16x4, __builtin_amdgcn_ds_read_tr16_b64_v4i16((LAS s16x4*)(vp + 2048))); }
;             __builtin_amdgcn_sched_barrier(0);
;             f32x4 s[2][2];
; #pragma unroll
;             for (int jj = 0; jj < 2; ++jj)
; #pragma unroll
;                 for (int kt = 0; kt < 2; ++kt) { f32x4 a = (MODE == 0) ? bb[jj][kt] + mneg[jj][kt] : bb[jj][kt];
;                     a = __builtin_amdgcn_mfma_f32_16x16x32_bf16(kf[jj][kt][0], qf[jj][0], a, 0, 0, 0);
;                     s[jj][kt] = __builtin_amdgcn_mfma_f32_16x16x32_bf16(kf[jj][kt][1], qf[jj][1], a, 0, 0, 0); }
;             u32x4 pw[2];
; #pragma unroll
;             for (int jj = 0; jj < 2; ++jj) {
;                 const float tm = vmax3(vmax3(s[jj][0][0], s[jj][0][1], s[jj][0][2]), vmax3(s[jj][0][3], s[jj][1][0], s[jj][1][1]), vmax3(s[jj][1][2], s[jj][1][3], s[jj][1][3]));
;                 const float mn = quad_max3(mrun[jj], tm);
;                 const float alpha = __builtin_amdgcn_exp2f(mrun[jj] - mn);
;                 mrun[jj] = mn;
;                 float rsum = 0.f;
; #pragma unroll
;                 for (int kt = 0; kt < 2; ++kt)
; #pragma unroll
;                     for (int e = 0; e < 4; ++e) { s[jj][kt][e] = __builtin_amdgcn_exp2f(s[jj][kt][e] - mn); rsum += s[jj][kt][e]; }
;                 lrun[jj] = lrun[jj] * alpha + rsum;
; #pragma unroll
.LBB0_278:
	s_sub_i32 s52, s25, s23
	v_lshlrev_b32_e32 v94, 5, v93
	s_add_i32 s0, s23, 7
	v_xor_b32_e32 v95, 32, v94
	v_xor_b32_e32 v96, 64, v94
	s_cmp_gt_u32 s0, 7
	v_xor_b32_e32 v97, 0x60, v94
	s_cbranch_scc1 .LBB0_291
	s_lshl_b32 s0, s86, 14
	s_add_i32 s0, s0, 0
	v_add_u32_e32 v0, s0, v89
	s_lshl_b32 s14, s52, 7
	v_add_u32_e32 v2, s0, v88
	ds_read_b128 v[6:9], v0
	ds_read_b128 v[10:13], v0 offset:2048
	ds_read_b128 v[14:17], v2
	ds_read_b128 v[34:37], v2 offset:2048
	v_add_u32_e32 v0, s0, v92
	s_add_i32 s14, s24, s14
	v_add_u32_e32 v2, s0, v91
	ds_read_b128 v[38:41], v0
	ds_read_b128 v[42:45], v0 offset:2048
	ds_read_b128 v[46:49], v2
	ds_read_b128 v[50:53], v2 offset:2048
	v_lshl_add_u32 v0, v87, 4, s14
	ds_read_b128 v[54:57], v0
	ds_read_b128 v[58:61], v0 offset:64
	v_lshl_add_u32 v0, v90, 4, s14
	ds_read_b128 v[62:65], v0
	ds_read_b128 v[66:69], v0 offset:64
	v_add3_u32 v0, v86, v122, s0
	v_add_u32_e32 v2, v0, v94
	v_add_u32_e32 v3, v0, v95
	ds_read_b64_tr_b16 v[70:71], v2 offset:8192
	ds_read_b64_tr_b16 v[72:73], v2 offset:10240
	ds_read_b64_tr_b16 v[74:75], v3 offset:8192
	ds_read_b64_tr_b16 v[76:77], v3 offset:10240
	v_add_u32_e32 v2, v0, v96
	v_add_u32_e32 v0, v0, v97
	ds_read_b64_tr_b16 v[78:79], v2 offset:8192
	ds_read_b64_tr_b16 v[80:81], v2 offset:10240
	ds_read_b64_tr_b16 v[126:127], v0 offset:8192
	ds_read_b64_tr_b16 v[128:129], v0 offset:10240
	v_add3_u32 v0, v123, v122, s0
	v_add_u32_e32 v2, v0, v94
	v_add_u32_e32 v3, v0, v95
	ds_read_b64_tr_b16 v[130:131], v2 offset:8192
	ds_read_b64_tr_b16 v[132:133], v2 offset:10240
	ds_read_b64_tr_b16 v[134:135], v3 offset:8192
	ds_read_b64_tr_b16 v[136:137], v3 offset:10240
	v_add_u32_e32 v2, v0, v96
	v_add_u32_e32 v0, v0, v97
	ds_read_b64_tr_b16 v[138:139], v2 offset:8192
	ds_read_b64_tr_b16 v[140:141], v2 offset:10240
	ds_read_b64_tr_b16 v[2:3], v0 offset:8192
	ds_read_b64_tr_b16 v[4:5], v0 offset:10240
	s_waitcnt lgkmcnt(14)
	v_pk_add_f32 v[56:57], v[112:113], v[56:57]
	v_pk_add_f32 v[54:55], v[110:111], v[54:55]
	s_mov_b32 s0, 0xf149f2ca
	s_nop 0
	v_mfma_f32_16x16x32_bf16 v[6:9], v[6:9], v[30:33], v[54:57]
	s_nop 2
	v_pk_add_f32 v[56:57], v[114:115], v[60:61]
	v_pk_add_f32 v[54:55], v[108:109], v[58:59]
	v_mfma_f32_16x16x32_bf16 v[6:9], v[14:17], v[26:29], v[6:9]
	v_pk_add_f32 v[16:17], v[106:107], v[64:65]
	v_pk_add_f32 v[14:15], v[102:103], v[62:63]
	v_mfma_f32_16x16x32_bf16 v[10:13], v[10:13], v[30:33], v[54:57]
	v_mfma_f32_16x16x32_bf16 v[10:13], v[34:37], v[26:29], v[10:13]
	s_nop 2
	v_maximum3_f32 v0, v6, v7, v8
	v_pk_add_f32 v[56:57], v[104:105], v[68:69]
	v_pk_add_f32 v[54:55], v[100:101], v[66:67]
	v_mfma_f32_16x16x32_bf16 v[14:17], v[38:41], v[22:25], v[14:17]
	v_mfma_f32_16x16x32_bf16 v[14:17], v[46:49], v[18:21], v[14:17]
	v_maximum3_f32 v34, v9, v10, v11
	v_maximum3_f32 v35, v12, v13, v13
	v_maximum3_f32 v0, v0, v34, v35
	v_mov_b32_e32 v34, v0
	s_nop 1
	v_permlane16_swap_b32_e32 v0, v34
	v_maximum3_f32 v0, v0, v34, v34
	v_mov_b32_e32 v34, v0
	s_nop 1
	v_permlane32_swap_b32_e32 v0, v34
	v_maximum3_f32 v125, v0, s0, v34
	v_mfma_f32_16x16x32_bf16 v[34:37], v[42:45], v[22:25], v[54:57]
	v_pk_add_f32 v[200:201], v[6:7], v[124:125] op_sel:[0,1] op_sel_hi:[1,1] neg_lo:[0,1] neg_hi:[0,1]
	v_pk_add_f32 v[202:203], v[8:9], v[124:125] op_sel:[0,1] op_sel_hi:[1,1] neg_lo:[0,1] neg_hi:[0,1]
	v_pk_add_f32 v[204:205], v[10:11], v[124:125] op_sel:[0,1] op_sel_hi:[1,1] neg_lo:[0,1] neg_hi:[0,1]
	v_pk_add_f32 v[206:207], v[12:13], v[124:125] op_sel:[0,1] op_sel_hi:[1,1] neg_lo:[0,1] neg_hi:[0,1]
	v_exp_f32_e32 v38, v200
	v_mfma_f32_16x16x32_bf16 v[34:37], v[50:53], v[18:21], v[34:37]
	v_exp_f32_e32 v40, v201
	v_exp_f32_e32 v42, v202
	v_sub_f32_e32 v0, 0xf149f2ca, v125
	v_exp_f32_e32 v66, v203
	v_exp_f32_e32 v68, v204
	v_exp_f32_e32 v146, v0
	v_maximum3_f32 v0, v14, v15, v16
	v_maximum3_f32 v10, v17, v34, v35
	v_maximum3_f32 v11, v36, v37, v37
	v_maximum3_f32 v0, v0, v10, v11
	v_mov_b32_e32 v10, v0
	s_nop 1
	v_permlane16_swap_b32_e32 v0, v10
	v_maximum3_f32 v0, v0, v10, v10
	v_mov_b32_e32 v10, v0
	s_nop 1
	v_permlane32_swap_b32_e32 v0, v10
	v_maximum3_f32 v124, v0, s0, v10
	v_exp_f32_e32 v98, v205
	v_sub_f32_e32 v0, 0xf149f2ca, v124
	v_exp_f32_e32 v142, v206
	v_pk_add_f32 v[208:209], v[14:15], v[124:125] op_sel_hi:[1,0] neg_lo:[0,1] neg_hi:[0,1]
	v_pk_add_f32 v[210:211], v[16:17], v[124:125] op_sel_hi:[1,0] neg_lo:[0,1] neg_hi:[0,1]
	v_pk_add_f32 v[212:213], v[34:35], v[124:125] op_sel_hi:[1,0] neg_lo:[0,1] neg_hi:[0,1]
	v_pk_add_f32 v[214:215], v[36:37], v[124:125] op_sel_hi:[1,0] neg_lo:[0,1] neg_hi:[0,1]
	v_exp_f32_e32 v147, v0
	v_exp_f32_e32 v144, v207
	v_exp_f32_e32 v39, v208
	v_exp_f32_e32 v41, v209
	v_exp_f32_e32 v43, v210
	v_exp_f32_e32 v69, v212
	v_exp_f32_e32 v67, v211
	v_pk_mul_f32 v[10:11], v[146:147], 0 op_sel_hi:[1,0]
	v_exp_f32_e32 v99, v213
	v_cvt_pk_bf16_f32 v6, v38, v40
	v_cvt_pk_bf16_f32 v7, v42, v66
	v_cvt_pk_bf16_f32 v8, v68, v98
	v_cvt_pk_bf16_f32 v9, v142, v144
	v_mov_b32_e32 v14, v10
	v_mov_b32_e32 v15, v10
	v_mov_b32_e32 v16, v10
	v_mov_b32_e32 v17, v10
	v_exp_f32_e32 v143, v214
	v_mfma_f32_16x16x32_bf16 v[54:57], v[70:73], v[6:9], v[14:17]
	v_exp_f32_e32 v145, v215
	v_mov_b32_e32 v10, v11
	v_mov_b32_e32 v12, v11
	s_setprio 1
	s_waitcnt lgkmcnt(12)
	v_mfma_f32_16x16x32_bf16 v[62:65], v[74:77], v[6:9], v[14:17]
	v_mov_b32_e32 v13, v11
	v_cvt_pk_bf16_f32 v34, v39, v41
	v_cvt_pk_bf16_f32 v35, v43, v67
	s_waitcnt lgkmcnt(10)
	v_mfma_f32_16x16x32_bf16 v[58:61], v[78:81], v[6:9], v[14:17]
	v_cvt_pk_bf16_f32 v36, v69, v99
	v_cvt_pk_bf16_f32 v37, v143, v145
	s_waitcnt lgkmcnt(8)
	v_mfma_f32_16x16x32_bf16 v[50:53], v[126:129], v[6:9], v[14:17]
	v_add_f32_e64 v6, v38, 0
	v_add_f32_e64 v7, v39, 0
	v_pk_add_f32 v[6:7], v[40:41], v[6:7]
	s_waitcnt lgkmcnt(6)
	v_mfma_f32_16x16x32_bf16 v[46:49], v[130:133], v[34:37], v[10:13]
	v_pk_add_f32 v[6:7], v[42:43], v[6:7]
	v_pk_add_f32 v[6:7], v[66:67], v[6:7]
	s_waitcnt lgkmcnt(4)
	v_mfma_f32_16x16x32_bf16 v[42:45], v[134:137], v[34:37], v[10:13]
	v_pk_add_f32 v[6:7], v[68:69], v[6:7]
	v_pk_add_f32 v[6:7], v[98:99], v[6:7]
	s_waitcnt lgkmcnt(2)
	v_mfma_f32_16x16x32_bf16 v[38:41], v[138:141], v[34:37], v[10:13]
	v_pk_add_f32 v[6:7], v[142:143], v[6:7]
	v_pk_add_f32 v[6:7], v[144:145], v[6:7]
	s_waitcnt lgkmcnt(0)
	v_mfma_f32_16x16x32_bf16 v[34:37], v[2:5], v[34:37], v[10:13]
	s_setprio 0
	v_fma_f32 v98, v146, 0, v6
	v_fma_f32 v99, v147, 0, v7
	s_cmp_eq_u32 s41, 1
	s_cbranch_scc1 .LBB0_281
	s_branch .LBB0_292

; #define LAS __attribute__((address_space(3)))
; template <int MODE> ...
;     ...
;         if (t >= act0 && t < act0 + actn) {
;         const LAS unsigned char* Sl = ring + ((t + base) % 3) * SLOT;
; #pragma unroll
;         for (int hf = 0; hf < NH; ++hf) {
;             if (MODE == 1) { const int ks = ktok0 + 64 * t + 32 * hf;
;                 if (ks + 31 < qtok0 - 128 || ks > qtok0 + 31 + 128) continue; }
;             bf16x8 kf[2][2][2];
; #pragma unroll
;             for (int jj = 0; jj < 2; ++jj)
; #pragma unroll
;                 for (int kt = 0; kt < 2; ++kt)
; #pragma unroll
;                     for (int ks = 0; ks < 2; ++ks) kf[jj][kt][ks] = *(const LAS bf16x8*)(Sl + kad[jj][ks] + (32 * hf + 16 * kt) * 128);
;             f32x4 bb[2][2];
; #pragma unroll
;             for (int jj = 0; jj < 2; ++jj) { const LAS f32x4* bl = bcp + ((MODE == 0) ? (dr0 + t - act0) * 8 : 16 * t + 8 * hf) + bofs[jj];
; #pragma unroll
;                 for (int kt = 0; kt < 2; ++kt) bb[jj][kt] = bl[4 * kt]; }
;             s16x4 vlo[2][4], vhi[2][4];
; #pragma unroll
;             for (int jj = 0; jj < 2; ++jj)
; #pragma unroll
;                 for (int dt = 0; dt < 4; ++dt) { const LAS unsigned char* vp = Sl + vad[jj] + (32 * hf) * 128 + ((dt ^ sv) << 5);
;                     vlo[jj][dt] = __builtin_bit_cast(s16x4, __builtin_amdgcn_ds_read_tr16_b64_v4i16((LAS s16x4*)(vp)));
;                     vhi[jj][dt] = __builtin_bit_cast(s16x4, __builtin_amdgcn_ds_read_tr16_b64_v4i16((LAS s16x4*)(vp + 2048))); }
.LBB0_298:
	s_add_i32 s0, s86, 1
	s_mul_hi_i32 s14, s0, 0x55555556
	s_lshr_b32 s15, s14, 31
	s_add_i32 s14, s14, s15
	s_mul_i32 s14, s14, 3
	s_sub_i32 s0, s0, s14
	s_lshl_b32 s0, s0, 14
	s_add_i32 s0, s0, 0
	v_add_u32_e32 v0, s0, v89
	s_lshl_b32 s14, s52, 7
	v_add_u32_e32 v2, s0, v88
	ds_read_b128 v[126:129], v0
	ds_read_b128 v[130:133], v0 offset:2048
	ds_read_b128 v[134:137], v2
	ds_read_b128 v[138:141], v2 offset:2048
	v_add_u32_e32 v0, s0, v92
	s_add_i32 s14, s24, s14
	v_add_u32_e32 v2, s0, v91
	ds_read_b128 v[142:145], v0
	ds_read_b128 v[146:149], v0 offset:2048
	ds_read_b128 v[150:153], v2
	ds_read_b128 v[154:157], v2 offset:2048
	v_lshl_add_u32 v0, v87, 4, s14
	ds_read_b128 v[158:161], v0 offset:128
	ds_read_b128 v[162:165], v0 offset:192
	v_lshl_add_u32 v0, v90, 4, s14
	ds_read_b128 v[166:169], v0 offset:128
	ds_read_b128 v[170:173], v0 offset:192
	v_add3_u32 v0, v86, v122, s0
	v_add_u32_e32 v2, v0, v94
	v_add_u32_e32 v3, v0, v95
	ds_read_b64_tr_b16 v[78:79], v2 offset:8192
	ds_read_b64_tr_b16 v[80:81], v2 offset:10240
	ds_read_b64_tr_b16 v[74:75], v3 offset:8192
	ds_read_b64_tr_b16 v[76:77], v3 offset:10240
	v_add_u32_e32 v2, v0, v96
	v_add_u32_e32 v0, v0, v97
	ds_read_b64_tr_b16 v[70:71], v2 offset:8192
	ds_read_b64_tr_b16 v[72:73], v2 offset:10240
	ds_read_b64_tr_b16 v[66:67], v0 offset:8192
	ds_read_b64_tr_b16 v[68:69], v0 offset:10240
	v_add3_u32 v0, v123, v122, s0
	v_add_u32_e32 v2, v0, v94
	v_add_u32_e32 v3, v0, v95
	ds_read_b64_tr_b16 v[14:15], v2 offset:8192
	ds_read_b64_tr_b16 v[16:17], v2 offset:10240
	ds_read_b64_tr_b16 v[10:11], v3 offset:8192
	ds_read_b64_tr_b16 v[12:13], v3 offset:10240
	v_add_u32_e32 v2, v0, v96
	v_add_u32_e32 v0, v0, v97
	ds_read_b64_tr_b16 v[6:7], v2 offset:8192
	ds_read_b64_tr_b16 v[8:9], v2 offset:10240
	ds_read_b64_tr_b16 v[2:3], v0 offset:8192
	ds_read_b64_tr_b16 v[4:5], v0 offset:10240
	s_waitcnt lgkmcnt(14)
; __device__ __forceinline__ unsigned cvtpk(float lo, float hi) { f32x2 v = {lo, hi}; bf16x2_t b = __builtin_convertvector(v, bf16x2_t); return __builtin_bit_cast(unsigned, b); }
; __device__ __forceinline__ float vmax3(float a, float b, float c) { return __builtin_elementwise_maximum(__builtin_elementwise_maximum(a, b), c); }
; template <int MODE> ...
;     ...
;             f32x4 s[2][2];
; #pragma unroll
;             for (int jj = 0; jj < 2; ++jj)
; #pragma unroll
;                 for (int kt = 0; kt < 2; ++kt) { f32x4 a = (MODE == 0) ? bb[jj][kt] + mneg[jj][kt] : bb[jj][kt];
;                     a = __builtin_amdgcn_mfma_f32_16x16x32_bf16(kf[jj][kt][0], qf[jj][0], a, 0, 0, 0);
;                     s[jj][kt] = __builtin_amdgcn_mfma_f32_16x16x32_bf16(kf[jj][kt][1], qf[jj][1], a, 0, 0, 0); }
;             u32x4 pw[2];
; #pragma unroll
;             for (int jj = 0; jj < 2; ++jj) {
;                 const float tm = vmax3(vmax3(s[jj][0][0], s[jj][0][1], s[jj][0][2]), vmax3(s[jj][0][3], s[jj][1][0], s[jj][1][1]), vmax3(s[jj][1][2], s[jj][1][3], s[jj][1][3]));
;                 const float mn = quad_max3(mrun[jj], tm);
;                 const float alpha = __builtin_amdgcn_exp2f(mrun[jj] - mn);
;                 mrun[jj] = mn;
;                 float rsum = 0.f;
; #pragma unroll
;                 for (int kt = 0; kt < 2; ++kt)
; #pragma unroll
;                     for (int e = 0; e < 4; ++e) { s[jj][kt][e] = __builtin_amdgcn_exp2f(s[jj][kt][e] - mn); rsum += s[jj][kt][e]; }
;                 lrun[jj] = lrun[jj] * alpha + rsum;
; #pragma unroll
;                 for (int dt = 0; dt < 4; ++dt) o[jj][dt] *= alpha;
;                 pw[jj].x = cvtpk(s[jj][0][0], s[jj][0][1]); pw[jj].y = cvtpk(s[jj][0][2], s[jj][0][3]); pw[jj].z = cvtpk(s[jj][1][0], s[jj][1][1]); pw[jj].w = cvtpk(s[jj][1][2], s[jj][1][3]);
;             }
; #pragma unroll
;             for (int jj = 0; jj < 2; ++jj)
; #pragma unroll
;                 for (int dt = 0; dt < 4; ++dt) {
;                     const bf16x8 vf = (bf16x8){vlo[jj][dt][0], vlo[jj][dt][1], vlo[jj][dt][2], vlo[jj][dt][3], vhi[jj][dt][0], vhi[jj][dt][1], vhi[jj][dt][2], vhi[jj][dt][3]};
;                     o[jj][dt] = __builtin_amdgcn_mfma_f32_16x16x32_bf16(vf, __builtin_bit_cast(bf16x8, pw[jj]), o[jj][dt], 0, 0, 0); }
;             __builtin_amdgcn_sched_barrier(0);
	v_pk_add_f32 v[160:161], v[112:113], v[160:161]
	v_pk_add_f32 v[158:159], v[110:111], v[158:159]
	s_nop 1
	v_mfma_f32_16x16x32_bf16 v[126:129], v[126:129], v[30:33], v[158:161]
	s_nop 2
	v_pk_add_f32 v[160:161], v[114:115], v[164:165]
	v_pk_add_f32 v[158:159], v[108:109], v[162:163]
	v_mfma_f32_16x16x32_bf16 v[126:129], v[134:137], v[26:29], v[126:129]
	v_pk_add_f32 v[136:137], v[106:107], v[168:169]
	v_pk_add_f32 v[134:135], v[102:103], v[166:167]
	v_mfma_f32_16x16x32_bf16 v[130:133], v[130:133], v[30:33], v[158:161]
	v_mfma_f32_16x16x32_bf16 v[130:133], v[138:141], v[26:29], v[130:133]
	s_nop 2
	v_maximum3_f32 v0, v126, v127, v128
	v_pk_add_f32 v[160:161], v[104:105], v[172:173]
	v_pk_add_f32 v[158:159], v[100:101], v[170:171]
	v_mfma_f32_16x16x32_bf16 v[134:137], v[142:145], v[22:25], v[134:137]
	v_mfma_f32_16x16x32_bf16 v[134:137], v[150:153], v[18:21], v[134:137]
	v_maximum3_f32 v138, v129, v130, v131
	v_maximum3_f32 v139, v132, v133, v133
	v_maximum3_f32 v0, v0, v138, v139
	v_mov_b32_e32 v138, v0
	s_nop 1
	v_permlane16_swap_b32_e32 v0, v138
	v_maximum3_f32 v0, v0, v138, v138
	v_mov_b32_e32 v138, v0
	s_nop 1
	v_permlane32_swap_b32_e32 v0, v138
	v_maximum3_f32 v162, v125, v0, v138
	v_mfma_f32_16x16x32_bf16 v[138:141], v[146:149], v[22:25], v[158:161]
	v_sub_f32_e32 v0, v125, v162
	v_pk_add_f32 v[200:201], v[126:127], v[162:163] op_sel_hi:[1,0] neg_lo:[0,1] neg_hi:[0,1]
	v_pk_add_f32 v[202:203], v[128:129], v[162:163] op_sel_hi:[1,0] neg_lo:[0,1] neg_hi:[0,1]
	v_pk_add_f32 v[204:205], v[130:131], v[162:163] op_sel_hi:[1,0] neg_lo:[0,1] neg_hi:[0,1]
	v_pk_add_f32 v[206:207], v[132:133], v[162:163] op_sel_hi:[1,0] neg_lo:[0,1] neg_hi:[0,1]
	v_exp_f32_e32 v142, v200
	v_exp_f32_e32 v144, v201
	v_mfma_f32_16x16x32_bf16 v[138:141], v[154:157], v[18:21], v[138:141]
	v_exp_f32_e32 v146, v202
	v_exp_f32_e32 v148, v203
	v_exp_f32_e32 v130, v204
	v_exp_f32_e32 v150, v205
	v_exp_f32_e32 v132, v0
	v_exp_f32_e32 v152, v206
	v_exp_f32_e32 v154, v207
	v_maximum3_f32 v0, v134, v135, v136
	v_maximum3_f32 v125, v137, v138, v139
	v_maximum3_f32 v129, v140, v141, v141
	v_maximum3_f32 v0, v0, v125, v129
	v_mov_b32_e32 v125, v0
	s_nop 1
	v_permlane16_swap_b32_e32 v0, v125
	v_maximum3_f32 v0, v0, v125, v125
	v_mov_b32_e32 v125, v0
	s_nop 1
	v_permlane32_swap_b32_e32 v0, v125
	v_maximum3_f32 v156, v124, v0, v125
	v_pk_mul_f32 v[56:57], v[56:57], v[132:133] op_sel_hi:[1,0]
	v_pk_mul_f32 v[54:55], v[54:55], v[132:133] op_sel_hi:[1,0]
	v_pk_mul_f32 v[64:65], v[64:65], v[132:133] op_sel_hi:[1,0]
	v_pk_mul_f32 v[62:63], v[62:63], v[132:133] op_sel_hi:[1,0]
	v_pk_mul_f32 v[60:61], v[60:61], v[132:133] op_sel_hi:[1,0]
	v_pk_mul_f32 v[58:59], v[58:59], v[132:133] op_sel_hi:[1,0]
	v_pk_mul_f32 v[52:53], v[52:53], v[132:133] op_sel_hi:[1,0]
	v_pk_mul_f32 v[50:51], v[50:51], v[132:133] op_sel_hi:[1,0]
	v_pk_add_f32 v[208:209], v[134:135], v[156:157] op_sel_hi:[1,0] neg_lo:[0,1] neg_hi:[0,1]
	v_pk_add_f32 v[210:211], v[136:137], v[156:157] op_sel_hi:[1,0] neg_lo:[0,1] neg_hi:[0,1]
	v_pk_add_f32 v[212:213], v[138:139], v[156:157] op_sel_hi:[1,0] neg_lo:[0,1] neg_hi:[0,1]
	v_pk_add_f32 v[214:215], v[140:141], v[156:157] op_sel_hi:[1,0] neg_lo:[0,1] neg_hi:[0,1]
	v_exp_f32_e32 v143, v208
	v_exp_f32_e32 v151, v213
	v_exp_f32_e32 v145, v209
	v_sub_f32_e32 v0, v124, v156
	v_exp_f32_e32 v147, v210
	v_exp_f32_e32 v153, v214
	v_exp_f32_e32 v149, v211
	v_exp_f32_e32 v155, v215
	v_exp_f32_e32 v133, v0
	v_exp_f32_e32 v131, v212
	v_cvt_pk_bf16_f32 v126, v142, v144
	v_cvt_pk_bf16_f32 v127, v146, v148
	v_cvt_pk_bf16_f32 v128, v130, v150
	v_cvt_pk_bf16_f32 v129, v152, v154
	v_pk_add_f32 v[124:125], v[142:143], 0 op_sel_hi:[1,0]
	v_mov_b32_e32 v0, v133
	v_pk_add_f32 v[124:125], v[144:145], v[124:125]
	s_setprio 1
	s_waitcnt lgkmcnt(10)
	v_mfma_f32_16x16x32_bf16 v[58:61], v[70:73], v[126:129], v[58:61]
	v_pk_mul_f32 v[48:49], v[48:49], v[0:1] op_sel_hi:[1,0]
	v_pk_mul_f32 v[46:47], v[46:47], v[0:1] op_sel_hi:[1,0]
	v_cvt_pk_bf16_f32 v70, v143, v145
	v_cvt_pk_bf16_f32 v71, v147, v149
	v_cvt_pk_bf16_f32 v72, v131, v151
	v_cvt_pk_bf16_f32 v73, v153, v155
	v_mfma_f32_16x16x32_bf16 v[54:57], v[78:81], v[126:129], v[54:57]
	v_pk_add_f32 v[78:79], v[146:147], v[124:125]
	v_pk_add_f32 v[78:79], v[148:149], v[78:79]
	s_waitcnt lgkmcnt(6)
	v_mfma_f32_16x16x32_bf16 v[46:49], v[14:17], v[70:73], v[46:49]
	v_pk_mul_f32 v[16:17], v[44:45], v[0:1] op_sel_hi:[1,0]
	v_pk_mul_f32 v[14:15], v[42:43], v[0:1] op_sel_hi:[1,0]
	v_mfma_f32_16x16x32_bf16 v[62:65], v[74:77], v[126:129], v[62:65]
	v_pk_add_f32 v[74:75], v[130:131], v[78:79]
	v_pk_add_f32 v[74:75], v[150:151], v[74:75]
	s_waitcnt lgkmcnt(4)
	v_mfma_f32_16x16x32_bf16 v[42:45], v[10:13], v[70:73], v[14:17]
	v_pk_mul_f32 v[12:13], v[40:41], v[0:1] op_sel_hi:[1,0]
	v_pk_mul_f32 v[10:11], v[38:39], v[0:1] op_sel_hi:[1,0]
	v_mfma_f32_16x16x32_bf16 v[50:53], v[66:69], v[126:129], v[50:53]
	v_pk_add_f32 v[66:67], v[152:153], v[74:75]
	v_pk_add_f32 v[14:15], v[154:155], v[66:67]
	s_waitcnt lgkmcnt(2)
	v_mfma_f32_16x16x32_bf16 v[38:41], v[6:9], v[70:73], v[10:13]
	v_pk_mul_f32 v[8:9], v[36:37], v[0:1] op_sel_hi:[1,0]
	v_pk_mul_f32 v[6:7], v[34:35], v[0:1] op_sel_hi:[1,0]
	v_pk_fma_f32 v[98:99], v[98:99], v[132:133], v[14:15]
	s_waitcnt lgkmcnt(0)
	v_mfma_f32_16x16x32_bf16 v[34:37], v[2:5], v[70:73], v[6:9]
	s_setprio 0
	v_mov_b32_e32 v125, v162
	v_mov_b32_e32 v124, v156
	s_cmp_eq_u32 s41, 2
	s_cbranch_scc1 .LBB0_281

; template <int MODE> ...
;     ...
;         if (t >= act0 && t < act0 + actn) {
;         const LAS unsigned char* Sl = ring + ((t + base) % 3) * SLOT;
; #pragma unroll
;         for (int hf = 0; hf < NH; ++hf) {
;             if (MODE == 1) { const int ks = ktok0 + 64 * t + 32 * hf;
;                 if (ks + 31 < qtok0 - 128 || ks > qtok0 + 31 + 128) continue; }
;             bf16x8 kf[2][2][2];
; #pragma unroll
;             for (int jj = 0; jj < 2; ++jj)
; #pragma unroll
;                 for (int kt = 0; kt < 2; ++kt)
; #pragma unroll
;                     for (int ks = 0; ks < 2; ++ks) kf[jj][kt][ks] = *(const LAS bf16x8*)(Sl + kad[jj][ks] + (32 * hf + 16 * kt) * 128);
;             f32x4 bb[2][2];
; #pragma unroll
;             for (int jj = 0; jj < 2; ++jj) { const LAS f32x4* bl = bcp + ((MODE == 0) ? (dr0 + t - act0) * 8 : 16 * t + 8 * hf) + bofs[jj];
; #pragma unroll
;                 for (int kt = 0; kt < 2; ++kt) bb[jj][kt] = bl[4 * kt]; }
;             s16x4 vlo[2][4], vhi[2][4];
; #pragma unroll
;             for (int jj = 0; jj < 2; ++jj)
; #pragma unroll
;                 for (int dt = 0; dt < 4; ++dt) { const LAS unsigned char* vp = Sl + vad[jj] + (32 * hf) * 128 + ((dt ^ sv) << 5);
;                     vlo[jj][dt] = __builtin_bit_cast(s16x4, __builtin_amdgcn_ds_read_tr16_b64_v4i16((LAS s16x4*)(vp)));
;                     vhi[jj][dt] = __builtin_bit_cast(s16x4, __builtin_amdgcn_ds_read_tr16_b64_v4i16((LAS s16x4*)(vp + 2048))); }
;             __builtin_amdgcn_sched_barrier(0);
;             f32x4 s[2][2];
; #pragma unroll
;             for (int jj = 0; jj < 2; ++jj)
; #pragma unroll
;                 for (int kt = 0; kt < 2; ++kt) { f32x4 a = (MODE == 0) ? bb[jj][kt] + mneg[jj][kt] : bb[jj][kt];
;                     a = __builtin_amdgcn_mfma_f32_16x16x32_bf16(kf[jj][kt][0], qf[jj][0], a, 0, 0, 0);
;                     s[jj][kt] = __builtin_amdgcn_mfma_f32_16x16x32_bf16(kf[jj][kt][1], qf[jj][1], a, 0, 0, 0); }
;             u32x4 pw[2];
; #pragma unroll
;             for (int jj = 0; jj < 2; ++jj) {
;                 const float tm = vmax3(vmax3(s[jj][0][0], s[jj][0][1], s[jj][0][2]), vmax3(s[jj][0][3], s[jj][1][0], s[jj][1][1]), vmax3(s[jj][1][2], s[jj][1][3], s[jj][1][3]));
;                 const float mn = quad_max3(mrun[jj], tm);
;                 const float alpha = __builtin_amdgcn_exp2f(mrun[jj] - mn);
;                 mrun[jj] = mn;
.LBB0_343:
	s_add_i32 s0, s86, s65
	s_mul_hi_i32 s14, s0, 0x55555556
	s_lshr_b32 s15, s14, 31
	s_add_i32 s14, s14, s15
	s_mul_i32 s14, s14, 3
	s_sub_i32 s0, s0, s14
	s_lshl_b32 s0, s0, 14
	s_add_i32 s0, s0, 0
	s_add_i32 s14, s27, 31
	s_cmp_lt_i32 s14, s41
	s_cselect_b64 s[50:51], -1, 0
	s_cmp_gt_i32 s27, s45
	s_cselect_b64 s[52:53], -1, 0
	s_or_b64 s[50:51], s[50:51], s[52:53]
	v_add_u32_e32 v0, s0, v78
	s_and_b64 vcc, exec, s[50:51]
	v_add_u32_e32 v98, s0, v70
	v_add_u32_e32 v97, s0, v71
	v_add_u32_e32 v96, s40, v80
	v_add_u32_e32 v85, s40, v79
	v_add_u32_e32 v84, v0, v74
	v_add_u32_e32 v83, v0, v75
	v_add_u32_e32 v81, v0, v76
	v_add_u32_e32 v0, v0, v77
	s_cbranch_vccnz .LBB0_345
	v_add_u32_e32 v2, 0x10000, v96
	v_add_u32_e32 v3, 0x10040, v96
	ds_read_b128 v[100:103], v98
	ds_read_b128 v[104:107], v98 offset:2048
	ds_read_b128 v[108:111], v97
	ds_read_b128 v[112:115], v97 offset:2048
	ds_read_b128 v[118:121], v2
	ds_read_b128 v[122:125], v3
	v_add_u32_e32 v2, 0x10000, v85
	v_add_u32_e32 v3, 0x10040, v85
	ds_read_b128 v[126:129], v2
	ds_read_b128 v[130:133], v3
	ds_read_b64_tr_b16 v[14:15], v84 offset:8192
	ds_read_b64_tr_b16 v[16:17], v84 offset:10240
	ds_read_b64_tr_b16 v[10:11], v83 offset:8192
	ds_read_b64_tr_b16 v[12:13], v83 offset:10240
	ds_read_b64_tr_b16 v[6:7], v81 offset:8192
	ds_read_b64_tr_b16 v[8:9], v81 offset:10240
	ds_read_b64_tr_b16 v[2:3], v0 offset:8192
	ds_read_b64_tr_b16 v[4:5], v0 offset:10240
	s_waitcnt lgkmcnt(11)
	v_mfma_f32_16x16x32_bf16 v[118:121], v[100:103], v[30:33], v[118:121]
	s_waitcnt lgkmcnt(10)
	v_mfma_f32_16x16x32_bf16 v[122:125], v[104:107], v[30:33], v[122:125]
	v_mfma_f32_16x16x32_bf16 v[118:121], v[108:111], v[26:29], v[118:121]
	v_mfma_f32_16x16x32_bf16 v[122:125], v[112:115], v[26:29], v[122:125]
	s_waitcnt lgkmcnt(9)
	v_mfma_f32_16x16x32_bf16 v[100:103], v[100:103], v[22:25], v[126:129]
	s_nop 4
	v_maximum3_f32 v99, v118, v119, v120
	v_mfma_f32_16x16x32_bf16 v[100:103], v[108:111], v[18:21], v[100:103]
	v_maximum3_f32 v108, v121, v122, v123
	v_maximum3_f32 v109, v124, v125, v125
	v_maximum3_f32 v99, v99, v108, v109
	s_waitcnt lgkmcnt(8)
	v_mfma_f32_16x16x32_bf16 v[104:107], v[104:107], v[22:25], v[130:133]
	v_mov_b32_e32 v108, v99
	s_nop 1
	v_permlane16_swap_b32_e32 v99, v108
	v_maximum3_f32 v99, v99, v108, v108
	v_mfma_f32_16x16x32_bf16 v[104:107], v[112:115], v[18:21], v[104:107]
	v_mov_b32_e32 v108, v99
	s_nop 1
	v_permlane32_swap_b32_e32 v99, v108
	v_maximum3_f32 v99, v82, v99, v108
	v_sub_f32_e32 v82, v82, v99
	v_exp_f32_e32 v130, v82
	v_maximum3_f32 v82, v100, v101, v102
	v_maximum3_f32 v113, v103, v104, v105
	v_maximum3_f32 v115, v106, v107, v107
	v_maximum3_f32 v82, v82, v113, v115
	v_mov_b32_e32 v113, v82
	s_nop 1
	v_permlane16_swap_b32_e32 v82, v113
	v_maximum3_f32 v82, v82, v113, v113
	v_mov_b32_e32 v113, v82
	s_nop 1
	v_permlane32_swap_b32_e32 v82, v113
	v_maximum3_f32 v117, v95, v82, v113
	v_pk_add_f32 v[200:201], v[118:119], v[98:99] op_sel:[0,1] op_sel_hi:[1,1] neg_lo:[0,1] neg_hi:[0,1]
	v_pk_add_f32 v[202:203], v[120:121], v[98:99] op_sel:[0,1] op_sel_hi:[1,1] neg_lo:[0,1] neg_hi:[0,1]
	v_pk_add_f32 v[204:205], v[122:123], v[98:99] op_sel:[0,1] op_sel_hi:[1,1] neg_lo:[0,1] neg_hi:[0,1]
	v_pk_add_f32 v[206:207], v[124:125], v[98:99] op_sel:[0,1] op_sel_hi:[1,1] neg_lo:[0,1] neg_hi:[0,1]
	v_sub_f32_e32 v82, v95, v117
	v_pk_add_f32 v[208:209], v[100:101], v[116:117] op_sel:[0,1] op_sel_hi:[1,1] neg_lo:[0,1] neg_hi:[0,1]
	v_pk_add_f32 v[210:211], v[102:103], v[116:117] op_sel:[0,1] op_sel_hi:[1,1] neg_lo:[0,1] neg_hi:[0,1]
	v_pk_add_f32 v[212:213], v[104:105], v[116:117] op_sel:[0,1] op_sel_hi:[1,1] neg_lo:[0,1] neg_hi:[0,1]
	v_pk_add_f32 v[214:215], v[106:107], v[116:117] op_sel:[0,1] op_sel_hi:[1,1] neg_lo:[0,1] neg_hi:[0,1]
	v_exp_f32_e32 v112, v200
	v_exp_f32_e32 v113, v208
	v_exp_f32_e32 v114, v201
	v_exp_f32_e32 v115, v209
	v_exp_f32_e32 v118, v202
	v_exp_f32_e32 v119, v210
	v_exp_f32_e32 v120, v203
	v_exp_f32_e32 v121, v211
	v_exp_f32_e32 v122, v204
	v_exp_f32_e32 v123, v212
	v_pk_add_f32 v[100:101], v[112:113], 0 op_sel_hi:[1,0]
	v_exp_f32_e32 v126, v205
	v_exp_f32_e32 v127, v213
	v_pk_add_f32 v[100:101], v[114:115], v[100:101]
	v_exp_f32_e32 v124, v206
	v_exp_f32_e32 v125, v214
	v_pk_add_f32 v[100:101], v[118:119], v[100:101]
	v_exp_f32_e32 v128, v207
	v_pk_mul_f32 v[52:53], v[52:53], v[130:131] op_sel_hi:[1,0]
	v_pk_mul_f32 v[50:51], v[50:51], v[130:131] op_sel_hi:[1,0]
	v_pk_mul_f32 v[56:57], v[56:57], v[130:131] op_sel_hi:[1,0]
	v_pk_mul_f32 v[54:55], v[54:55], v[130:131] op_sel_hi:[1,0]
	v_pk_mul_f32 v[60:61], v[60:61], v[130:131] op_sel_hi:[1,0]
	v_pk_mul_f32 v[58:59], v[58:59], v[130:131] op_sel_hi:[1,0]
	v_pk_mul_f32 v[64:65], v[64:65], v[130:131] op_sel_hi:[1,0]
	v_pk_mul_f32 v[62:63], v[62:63], v[130:131] op_sel_hi:[1,0]
	v_exp_f32_e32 v129, v215
	v_pk_add_f32 v[100:101], v[120:121], v[100:101]
	v_exp_f32_e32 v131, v82
	v_pk_add_f32 v[100:101], v[122:123], v[100:101]
	v_cvt_pk_bf16_f32 v108, v112, v114
	v_pk_add_f32 v[100:101], v[126:127], v[100:101]
	v_mov_b32_e32 v82, v131
	v_pk_add_f32 v[100:101], v[124:125], v[100:101]
	v_cvt_pk_bf16_f32 v109, v118, v120
	v_pk_add_f32 v[100:101], v[128:129], v[100:101]
	v_cvt_pk_bf16_f32 v110, v122, v126
	v_cvt_pk_bf16_f32 v111, v124, v128
	v_pk_fma_f32 v[88:89], v[88:89], v[130:131], v[100:101]
	v_pk_mul_f32 v[36:37], v[36:37], v[82:83] op_sel_hi:[1,0]
	v_pk_mul_f32 v[34:35], v[34:35], v[82:83] op_sel_hi:[1,0]
	v_pk_mul_f32 v[40:41], v[40:41], v[82:83] op_sel_hi:[1,0]
	v_pk_mul_f32 v[38:39], v[38:39], v[82:83] op_sel_hi:[1,0]
	v_pk_mul_f32 v[44:45], v[44:45], v[82:83] op_sel_hi:[1,0]
	v_pk_mul_f32 v[42:43], v[42:43], v[82:83] op_sel_hi:[1,0]
	v_pk_mul_f32 v[48:49], v[48:49], v[82:83] op_sel_hi:[1,0]
	v_pk_mul_f32 v[46:47], v[46:47], v[82:83] op_sel_hi:[1,0]
	v_cvt_pk_bf16_f32 v100, v113, v115
	v_cvt_pk_bf16_f32 v101, v119, v121
	v_cvt_pk_bf16_f32 v102, v123, v127
	v_cvt_pk_bf16_f32 v103, v125, v129
	s_setprio 1
	s_waitcnt lgkmcnt(6)
	v_mfma_f32_16x16x32_bf16 v[50:53], v[14:17], v[108:111], v[50:53]
	s_waitcnt lgkmcnt(4)
	v_mfma_f32_16x16x32_bf16 v[54:57], v[10:13], v[108:111], v[54:57]
	s_waitcnt lgkmcnt(2)
	v_mfma_f32_16x16x32_bf16 v[58:61], v[6:9], v[108:111], v[58:61]
	s_waitcnt lgkmcnt(0)
	v_mfma_f32_16x16x32_bf16 v[62:65], v[2:5], v[108:111], v[62:65]
	v_mfma_f32_16x16x32_bf16 v[34:37], v[14:17], v[100:103], v[34:37]
	v_mfma_f32_16x16x32_bf16 v[38:41], v[10:13], v[100:103], v[38:41]
	v_mfma_f32_16x16x32_bf16 v[42:45], v[6:9], v[100:103], v[42:45]
	v_mfma_f32_16x16x32_bf16 v[46:49], v[2:5], v[100:103], v[46:49]
	s_setprio 0
	v_mov_b32_e32 v82, v99
	v_mov_b32_e32 v95, v117
; #define LAS __attribute__((address_space(3)))
; template <int MODE> ...
;     ...
;             if (MODE == 1) { const int ks = ktok0 + 64 * t + 32 * hf;
;                 if (ks + 31 < qtok0 - 128 || ks > qtok0 + 31 + 128) continue; }
;             bf16x8 kf[2][2][2];
; #pragma unroll
;             for (int jj = 0; jj < 2; ++jj)
; #pragma unroll
;                 for (int kt = 0; kt < 2; ++kt)
; #pragma unroll
;                     for (int ks = 0; ks < 2; ++ks) kf[jj][kt][ks] = *(const LAS bf16x8*)(Sl + kad[jj][ks] + (32 * hf + 16 * kt) * 128);
;             f32x4 bb[2][2];
; #pragma unroll
;             for (int jj = 0; jj < 2; ++jj) { const LAS f32x4* bl = bcp + ((MODE == 0) ? (dr0 + t - act0) * 8 : 16 * t + 8 * hf) + bofs[jj];
; #pragma unroll
;                 for (int kt = 0; kt < 2; ++kt) bb[jj][kt] = bl[4 * kt]; }
;             s16x4 vlo[2][4], vhi[2][4];
; #pragma unroll
;             for (int jj = 0; jj < 2; ++jj)
; #pragma unroll
;                 for (int dt = 0; dt < 4; ++dt) { const LAS unsigned char* vp = Sl + vad[jj] + (32 * hf) * 128 + ((dt ^ sv) << 5);
;                     vlo[jj][dt] = __builtin_bit_cast(s16x4, __builtin_amdgcn_ds_read_tr16_b64_v4i16((LAS s16x4*)(vp)));
;                     vhi[jj][dt] = __builtin_bit_cast(s16x4, __builtin_amdgcn_ds_read_tr16_b64_v4i16((LAS s16x4*)(vp + 2048))); }
;             __builtin_amdgcn_sched_barrier(0);
;             f32x4 s[2][2];
; #pragma unroll
;             for (int jj = 0; jj < 2; ++jj)
; #pragma unroll
;                 for (int kt = 0; kt < 2; ++kt) { f32x4 a = (MODE == 0) ? bb[jj][kt] + mneg[jj][kt] : bb[jj][kt];
;                     a = __builtin_amdgcn_mfma_f32_16x16x32_bf16(kf[jj][kt][0], qf[jj][0], a, 0, 0, 0);
;                     s[jj][kt] = __builtin_amdgcn_mfma_f32_16x16x32_bf16(kf[jj][kt][1], qf[jj][1], a, 0, 0, 0); }
;             u32x4 pw[2];
; #pragma unroll
;             for (int jj = 0; jj < 2; ++jj) {
;                 const float tm = vmax3(vmax3(s[jj][0][0], s[jj][0][1], s[jj][0][2]), vmax3(s[jj][0][3], s[jj][1][0], s[jj][1][1]), vmax3(s[jj][1][2], s[jj][1][3], s[jj][1][3]));
;                 const float mn = quad_max3(mrun[jj], tm);
;                 const float alpha = __builtin_amdgcn_exp2f(mrun[jj] - mn);
;                 mrun[jj] = mn;
;                 float rsum = 0.f;
; #pragma unroll
;                 for (int kt = 0; kt < 2; ++kt)
; #pragma unroll
.LBB0_345:
	s_add_i32 s0, s27, 32
	s_add_i32 s14, s27, 63
	s_cmp_lt_i32 s14, s41
	s_cselect_b64 s[50:51], -1, 0
	s_cmp_gt_i32 s0, s45
	s_cselect_b64 s[52:53], -1, 0
	s_or_b64 s[50:51], s[50:51], s[52:53]
	s_and_b64 vcc, exec, s[50:51]
	s_cbranch_vccnz .LBB0_333
	v_add_u32_e32 v2, 0x10080, v96
	v_add_u32_e32 v3, 0x100c0, v96
	ds_read_b128 v[100:103], v98 offset:4096
	ds_read_b128 v[104:107], v98 offset:6144
	ds_read_b128 v[108:111], v97 offset:4096
	ds_read_b128 v[112:115], v97 offset:6144
	ds_read_b128 v[96:99], v2
	ds_read_b128 v[118:121], v3
	v_add_u32_e32 v2, 0x10080, v85
	v_add_u32_e32 v3, 0x100c0, v85
	ds_read_b128 v[122:125], v2
	ds_read_b128 v[126:129], v3
	ds_read_b64_tr_b16 v[14:15], v84 offset:12288
	ds_read_b64_tr_b16 v[16:17], v84 offset:14336
	ds_read_b64_tr_b16 v[10:11], v83 offset:12288
	ds_read_b64_tr_b16 v[12:13], v83 offset:14336
	ds_read_b64_tr_b16 v[6:7], v81 offset:12288
	ds_read_b64_tr_b16 v[8:9], v81 offset:14336
	ds_read_b64_tr_b16 v[2:3], v0 offset:12288
	ds_read_b64_tr_b16 v[4:5], v0 offset:14336
	s_waitcnt lgkmcnt(11)
	v_mfma_f32_16x16x32_bf16 v[96:99], v[100:103], v[30:33], v[96:99]
	s_waitcnt lgkmcnt(10)
	v_mfma_f32_16x16x32_bf16 v[118:121], v[104:107], v[30:33], v[118:121]
	v_mfma_f32_16x16x32_bf16 v[96:99], v[108:111], v[26:29], v[96:99]
	v_mfma_f32_16x16x32_bf16 v[118:121], v[112:115], v[26:29], v[118:121]
	s_waitcnt lgkmcnt(9)
	v_mfma_f32_16x16x32_bf16 v[100:103], v[100:103], v[22:25], v[122:125]
	s_nop 4
	v_maximum3_f32 v0, v96, v97, v98
	v_maximum3_f32 v81, v99, v118, v119
	v_maximum3_f32 v83, v120, v121, v121
	v_maximum3_f32 v0, v0, v81, v83
	v_mov_b32_e32 v81, v0
	s_waitcnt lgkmcnt(8)
	v_mfma_f32_16x16x32_bf16 v[104:107], v[104:107], v[22:25], v[126:129]
	v_permlane16_swap_b32_e32 v0, v81
	v_maximum3_f32 v0, v0, v81, v81
	v_mov_b32_e32 v81, v0
	s_nop 1
	v_permlane32_swap_b32_e32 v0, v81
	v_mfma_f32_16x16x32_bf16 v[100:103], v[108:111], v[18:21], v[100:103]
	v_maximum3_f32 v81, v82, v0, v81
	v_sub_f32_e32 v0, v82, v81
	v_pk_add_f32 v[200:201], v[96:97], v[80:81] op_sel:[0,1] op_sel_hi:[1,1] neg_lo:[0,1] neg_hi:[0,1]
	v_pk_add_f32 v[202:203], v[98:99], v[80:81] op_sel:[0,1] op_sel_hi:[1,1] neg_lo:[0,1] neg_hi:[0,1]
	v_pk_add_f32 v[204:205], v[118:119], v[80:81] op_sel:[0,1] op_sel_hi:[1,1] neg_lo:[0,1] neg_hi:[0,1]
	v_pk_add_f32 v[206:207], v[120:121], v[80:81] op_sel:[0,1] op_sel_hi:[1,1] neg_lo:[0,1] neg_hi:[0,1]
	v_mfma_f32_16x16x32_bf16 v[104:107], v[112:115], v[18:21], v[104:107]
	v_exp_f32_e32 v96, v200
	v_exp_f32_e32 v108, v201
	v_exp_f32_e32 v98, v202
	v_exp_f32_e32 v122, v0
	v_maximum3_f32 v0, v100, v101, v102
	v_maximum3_f32 v97, v103, v104, v105
	v_maximum3_f32 v99, v106, v107, v107
	v_maximum3_f32 v0, v0, v97, v99
	v_mov_b32_e32 v97, v0
	s_nop 1
	v_permlane16_swap_b32_e32 v0, v97
	v_maximum3_f32 v0, v0, v97, v97
	v_mov_b32_e32 v97, v0
	s_nop 1
	v_permlane32_swap_b32_e32 v0, v97
	v_maximum3_f32 v117, v95, v0, v97
	v_sub_f32_e32 v0, v95, v117
	v_pk_add_f32 v[208:209], v[100:101], v[116:117] op_sel:[0,1] op_sel_hi:[1,1] neg_lo:[0,1] neg_hi:[0,1]
	v_pk_add_f32 v[210:211], v[102:103], v[116:117] op_sel:[0,1] op_sel_hi:[1,1] neg_lo:[0,1] neg_hi:[0,1]
	v_pk_add_f32 v[212:213], v[104:105], v[116:117] op_sel:[0,1] op_sel_hi:[1,1] neg_lo:[0,1] neg_hi:[0,1]
	v_pk_add_f32 v[214:215], v[106:107], v[116:117] op_sel:[0,1] op_sel_hi:[1,1] neg_lo:[0,1] neg_hi:[0,1]
	v_exp_f32_e32 v97, v208
	v_exp_f32_e32 v109, v209
	v_exp_f32_e32 v99, v210
	v_exp_f32_e32 v110, v203
	v_exp_f32_e32 v111, v211
	v_exp_f32_e32 v112, v204
	v_exp_f32_e32 v113, v212
	v_exp_f32_e32 v114, v205
	v_exp_f32_e32 v115, v213
	v_exp_f32_e32 v118, v206
	v_pk_mul_f32 v[52:53], v[52:53], v[122:123] op_sel_hi:[1,0]
	v_pk_mul_f32 v[50:51], v[50:51], v[122:123] op_sel_hi:[1,0]
	v_pk_mul_f32 v[56:57], v[56:57], v[122:123] op_sel_hi:[1,0]
	v_pk_mul_f32 v[54:55], v[54:55], v[122:123] op_sel_hi:[1,0]
	v_pk_mul_f32 v[60:61], v[60:61], v[122:123] op_sel_hi:[1,0]
	v_pk_mul_f32 v[58:59], v[58:59], v[122:123] op_sel_hi:[1,0]
	v_pk_mul_f32 v[64:65], v[64:65], v[122:123] op_sel_hi:[1,0]
	v_pk_mul_f32 v[62:63], v[62:63], v[122:123] op_sel_hi:[1,0]
	v_exp_f32_e32 v119, v214
	v_exp_f32_e32 v123, v0
	v_exp_f32_e32 v120, v207
	v_pk_add_f32 v[100:101], v[96:97], 0 op_sel_hi:[1,0]
	v_exp_f32_e32 v121, v215
	v_pk_add_f32 v[100:101], v[108:109], v[100:101]
	v_mov_b32_e32 v0, v123
	v_pk_add_f32 v[100:101], v[98:99], v[100:101]
	v_cvt_pk_bf16_f32 v82, v96, v108
	v_pk_add_f32 v[100:101], v[110:111], v[100:101]
	v_cvt_pk_bf16_f32 v83, v98, v110
	v_cvt_pk_bf16_f32 v84, v112, v114
	v_cvt_pk_bf16_f32 v85, v118, v120
	v_pk_add_f32 v[100:101], v[112:113], v[100:101]
	v_pk_mul_f32 v[36:37], v[36:37], v[0:1] op_sel_hi:[1,0]
	v_pk_mul_f32 v[34:35], v[34:35], v[0:1] op_sel_hi:[1,0]
	v_pk_mul_f32 v[40:41], v[40:41], v[0:1] op_sel_hi:[1,0]
	v_pk_mul_f32 v[38:39], v[38:39], v[0:1] op_sel_hi:[1,0]
	v_pk_mul_f32 v[44:45], v[44:45], v[0:1] op_sel_hi:[1,0]
	v_pk_mul_f32 v[42:43], v[42:43], v[0:1] op_sel_hi:[1,0]
	v_pk_mul_f32 v[48:49], v[48:49], v[0:1] op_sel_hi:[1,0]
	v_pk_mul_f32 v[46:47], v[46:47], v[0:1] op_sel_hi:[1,0]
	v_cvt_pk_bf16_f32 v96, v97, v109
	v_cvt_pk_bf16_f32 v97, v99, v111
	v_cvt_pk_bf16_f32 v98, v113, v115
	v_cvt_pk_bf16_f32 v99, v119, v121
	v_pk_add_f32 v[100:101], v[114:115], v[100:101]
	s_setprio 1
	s_waitcnt lgkmcnt(6)
	v_mfma_f32_16x16x32_bf16 v[50:53], v[14:17], v[82:85], v[50:53]
	v_pk_add_f32 v[100:101], v[118:119], v[100:101]
	v_pk_add_f32 v[100:101], v[120:121], v[100:101]
	s_waitcnt lgkmcnt(4)
	v_mfma_f32_16x16x32_bf16 v[54:57], v[10:13], v[82:85], v[54:57]
	v_fma_f32 v88, v88, v122, v100
	v_fma_f32 v89, v89, v123, v101
	s_waitcnt lgkmcnt(2)
	v_mfma_f32_16x16x32_bf16 v[58:61], v[6:9], v[82:85], v[58:61]
	s_waitcnt lgkmcnt(0)
	v_mfma_f32_16x16x32_bf16 v[62:65], v[2:5], v[82:85], v[62:65]
	v_mfma_f32_16x16x32_bf16 v[34:37], v[14:17], v[96:99], v[34:37]
	v_mfma_f32_16x16x32_bf16 v[38:41], v[10:13], v[96:99], v[38:41]
	v_mfma_f32_16x16x32_bf16 v[42:45], v[6:9], v[96:99], v[42:45]
	v_mfma_f32_16x16x32_bf16 v[46:49], v[2:5], v[96:99], v[46:49]
	s_setprio 0
	v_mov_b32_e32 v95, v117
	v_mov_b32_e32 v82, v81
	s_branch .LBB0_333

; #define LAS __attribute__((address_space(3)))
; #define GAS __attribute__((address_space(1)))
; template <int MODE> ...
;     ...
;         if (t >= act0 && t < act0 + actn) {
;         const LAS unsigned char* Sl = ring + ((t + base) % 3) * SLOT;
; #pragma unroll
;         for (int hf = 0; hf < NH; ++hf) {
;             if (MODE == 1) { const int ks = ktok0 + 64 * t + 32 * hf;
;                 if (ks + 31 < qtok0 - 128 || ks > qtok0 + 31 + 128) continue; }
;     ...
;     bf16x8 qn[2][2];
;     { const GAS bf16_t* qs = nQ ? (const GAS bf16_t*)nQ : (const GAS bf16_t*)proj + (size_t)qtok0 * NIN + qcol;
; #pragma unroll
;       for (int jj = 0; jj < 2; ++jj)
; #pragma unroll
;           for (int ks = 0; ks < 2; ++ks) qn[jj][ks] = *(const GAS bf16x8*)(qs + (size_t)(16 * jj) * NIN + 32 * ks + qoff); }
.LBB0_356:
	v_lshl_add_u64 v[6:7], v[66:67], 1, s[38:39]
	global_load_dwordx4 v[2:5], v[6:7], off
	global_load_dwordx4 v[10:13], v[6:7], off offset:64
	v_add_co_u32_e32 v6, vcc, 0x12000, v6
	s_cmp_lt_i32 s5, 1
	s_nop 0
	v_addc_co_u32_e32 v7, vcc, 0, v7, vcc
	global_load_dwordx4 v[14:17], v[6:7], off
	s_nop 0
	global_load_dwordx4 v[6:9], v[6:7], off offset:64
	s_cbranch_scc1 .LBB0_361
	s_mul_i32 s0, s22, 0x600
	s_add_i32 s27, s0, 0
	s_add_i32 s0, s26, s86
	s_mul_hi_i32 s14, s0, 0x55555556
	s_lshr_b32 s15, s14, 31
	s_add_i32 s14, s14, s15
	s_mul_i32 s14, s14, 3
	s_sub_i32 s0, s0, s14
	s_lshl_b32 s30, s26, 6
	s_lshl_b32 s0, s0, 14
	s_add_i32 s14, s30, s24
	s_add_i32 s27, s27, 0x10000
	s_add_i32 s0, s0, 0
	s_lshl_b32 s26, s26, 8
	s_or_b32 s15, s14, 31
	s_add_i32 s31, s25, 0xffffff80
	s_cmp_lt_i32 s15, s31
	s_cselect_b64 s[38:39], -1, 0
	s_addk_i32 s25, 0x9f
	s_cmp_gt_i32 s14, s25
	s_cselect_b64 s[40:41], -1, 0
	s_or_b64 s[38:39], s[38:39], s[40:41]
	v_add_u32_e32 v100, s0, v70
	v_add_u32_e32 v99, s0, v71
	v_add3_u32 v66, v72, v73, s0
	s_movk_i32 s0, 0x60
	s_and_b64 vcc, exec, s[38:39]
	v_add_u32_e32 v98, v66, v74
	v_xad_u32 v97, v74, 32, v66
	v_xad_u32 v0, v74, 64, v66
	v_xad_u32 v96, v74, s0, v66
	s_cbranch_vccnz .LBB0_359
; template <int MODE> ...
;     ...
;             bf16x8 kf[2][2][2];
; #pragma unroll
;             for (int jj = 0; jj < 2; ++jj)
; #pragma unroll
;                 for (int kt = 0; kt < 2; ++kt)
; #pragma unroll
;                     for (int ks = 0; ks < 2; ++ks) kf[jj][kt][ks] = *(const LAS bf16x8*)(Sl + kad[jj][ks] + (32 * hf + 16 * kt) * 128);
;             f32x4 bb[2][2];
; #pragma unroll
;             for (int jj = 0; jj < 2; ++jj) { const LAS f32x4* bl = bcp + ((MODE == 0) ? (dr0 + t - act0) * 8 : 16 * t + 8 * hf) + bofs[jj];
; #pragma unroll
;                 for (int kt = 0; kt < 2; ++kt) bb[jj][kt] = bl[4 * kt]; }
;             s16x4 vlo[2][4], vhi[2][4];
; #pragma unroll
;             for (int jj = 0; jj < 2; ++jj)
; #pragma unroll
;                 for (int dt = 0; dt < 4; ++dt) { const LAS unsigned char* vp = Sl + vad[jj] + (32 * hf) * 128 + ((dt ^ sv) << 5);
;                     vlo[jj][dt] = __builtin_bit_cast(s16x4, __builtin_amdgcn_ds_read_tr16_b64_v4i16((LAS s16x4*)(vp)));
;                     vhi[jj][dt] = __builtin_bit_cast(s16x4, __builtin_amdgcn_ds_read_tr16_b64_v4i16((LAS s16x4*)(vp + 2048))); }
;             __builtin_amdgcn_sched_barrier(0);
;             f32x4 s[2][2];
; #pragma unroll
;             for (int jj = 0; jj < 2; ++jj)
; #pragma unroll
;                 for (int kt = 0; kt < 2; ++kt) { f32x4 a = (MODE == 0) ? bb[jj][kt] + mneg[jj][kt] : bb[jj][kt];
;                     a = __builtin_amdgcn_mfma_f32_16x16x32_bf16(kf[jj][kt][0], qf[jj][0], a, 0, 0, 0);
;                     s[jj][kt] = __builtin_amdgcn_mfma_f32_16x16x32_bf16(kf[jj][kt][1], qf[jj][1], a, 0, 0, 0); }
;             u32x4 pw[2];
; #pragma unroll
;             for (int jj = 0; jj < 2; ++jj) {
;                 const float tm = vmax3(vmax3(s[jj][0][0], s[jj][0][1], s[jj][0][2]), vmax3(s[jj][0][3], s[jj][1][0], s[jj][1][1]), vmax3(s[jj][1][2], s[jj][1][3], s[jj][1][3]));
;                 const float mn = quad_max3(mrun[jj], tm);
;                 const float alpha = __builtin_amdgcn_exp2f(mrun[jj] - mn);
;                 mrun[jj] = mn;
;                 float rsum = 0.f;
; #pragma unroll
;                 for (int kt = 0; kt < 2; ++kt)
; #pragma unroll
;                     for (int e = 0; e < 4; ++e) { s[jj][kt][e] = __builtin_amdgcn_exp2f(s[jj][kt][e] - mn); rsum += s[jj][kt][e]; }
;                 lrun[jj] = lrun[jj] * alpha + rsum;
; #pragma unroll
	s_add_i32 s0, s27, s26
	v_lshl_add_u32 v66, v93, 4, s0
	ds_read_b128 v[102:105], v100
	ds_read_b128 v[106:109], v100 offset:2048
	ds_read_b128 v[110:113], v99
	ds_read_b128 v[118:121], v99 offset:2048
	ds_read_b128 v[122:125], v66
	ds_read_b128 v[126:129], v66 offset:64
	v_lshl_add_u32 v66, v94, 4, s0
	ds_read_b128 v[130:133], v66
	ds_read_b128 v[134:137], v66 offset:64
	ds_read_b64_tr_b16 v[78:79], v98 offset:8192
	ds_read_b64_tr_b16 v[80:81], v98 offset:10240
	ds_read_b64_tr_b16 v[74:75], v97 offset:8192
	ds_read_b64_tr_b16 v[76:77], v97 offset:10240
	ds_read_b64_tr_b16 v[70:71], v0 offset:8192
	ds_read_b64_tr_b16 v[72:73], v0 offset:10240
	ds_read_b64_tr_b16 v[66:67], v96 offset:8192
	ds_read_b64_tr_b16 v[68:69], v96 offset:10240
	s_waitcnt lgkmcnt(11)
	v_mfma_f32_16x16x32_bf16 v[122:125], v[102:105], v[30:33], v[122:125]
	s_waitcnt lgkmcnt(10)
	v_mfma_f32_16x16x32_bf16 v[126:129], v[106:109], v[30:33], v[126:129]
	s_waitcnt lgkmcnt(9)
	v_mfma_f32_16x16x32_bf16 v[102:105], v[102:105], v[22:25], v[130:133]
	s_waitcnt lgkmcnt(8)
	v_mfma_f32_16x16x32_bf16 v[106:109], v[106:109], v[22:25], v[134:137]
	v_mfma_f32_16x16x32_bf16 v[102:105], v[110:113], v[18:21], v[102:105]
	v_mfma_f32_16x16x32_bf16 v[106:109], v[118:121], v[18:21], v[106:109]
	v_mfma_f32_16x16x32_bf16 v[122:125], v[110:113], v[26:29], v[122:125]
	s_nop 5
	v_maximum3_f32 v111, v102, v103, v104
	v_maximum3_f32 v113, v105, v106, v107
	v_maximum3_f32 v115, v108, v109, v109
	v_mfma_f32_16x16x32_bf16 v[126:129], v[118:121], v[26:29], v[126:129]
	v_maximum3_f32 v111, v111, v113, v115
	v_maximum3_f32 v83, v122, v123, v124
	v_mov_b32_e32 v113, v111
	s_nop 1
	v_permlane16_swap_b32_e32 v111, v113
	v_maximum3_f32 v111, v111, v113, v113
	s_nop 0
	v_maximum3_f32 v84, v125, v126, v127
	v_maximum3_f32 v85, v128, v129, v129
	v_maximum3_f32 v83, v83, v84, v85
	v_mov_b32_e32 v84, v83
	s_nop 1
	v_permlane16_swap_b32_e32 v83, v84
	v_maximum3_f32 v83, v83, v84, v84
	v_mov_b32_e32 v113, v111
	v_mov_b32_e32 v84, v83
	s_nop 0
	v_permlane32_swap_b32_e32 v111, v113
	v_permlane32_swap_b32_e32 v83, v84
	v_maximum3_f32 v117, v95, v111, v113
	v_maximum3_f32 v101, v82, v83, v84
	v_pk_add_f32 v[200:201], v[102:103], v[116:117] op_sel:[0,1] op_sel_hi:[1,1] neg_lo:[0,1] neg_hi:[0,1]
	v_pk_add_f32 v[202:203], v[104:105], v[116:117] op_sel:[0,1] op_sel_hi:[1,1] neg_lo:[0,1] neg_hi:[0,1]
	v_pk_add_f32 v[204:205], v[106:107], v[116:117] op_sel:[0,1] op_sel_hi:[1,1] neg_lo:[0,1] neg_hi:[0,1]
	v_pk_add_f32 v[206:207], v[108:109], v[116:117] op_sel:[0,1] op_sel_hi:[1,1] neg_lo:[0,1] neg_hi:[0,1]
	v_pk_add_f32 v[208:209], v[122:123], v[100:101] op_sel:[0,1] op_sel_hi:[1,1] neg_lo:[0,1] neg_hi:[0,1]
	v_pk_add_f32 v[210:211], v[124:125], v[100:101] op_sel:[0,1] op_sel_hi:[1,1] neg_lo:[0,1] neg_hi:[0,1]
	v_pk_add_f32 v[212:213], v[126:127], v[100:101] op_sel:[0,1] op_sel_hi:[1,1] neg_lo:[0,1] neg_hi:[0,1]
	v_pk_add_f32 v[214:215], v[128:129], v[100:101] op_sel:[0,1] op_sel_hi:[1,1] neg_lo:[0,1] neg_hi:[0,1]
	v_exp_f32_e32 v111, v200
	v_exp_f32_e32 v110, v208
	v_exp_f32_e32 v113, v201
	v_exp_f32_e32 v112, v209
	v_exp_f32_e32 v115, v202
	v_exp_f32_e32 v114, v210
	v_exp_f32_e32 v119, v203
	v_exp_f32_e32 v118, v211
	v_exp_f32_e32 v121, v204
	v_sub_f32_e32 v82, v82, v101
	v_exp_f32_e32 v120, v212
	v_exp_f32_e32 v123, v205
	v_exp_f32_e32 v122, v213
	v_exp_f32_e32 v128, v82
	v_pk_add_f32 v[130:131], v[110:111], 0 op_sel_hi:[1,0]
	v_exp_f32_e32 v125, v206
	v_exp_f32_e32 v127, v207
	v_pk_add_f32 v[102:103], v[112:113], v[130:131]
	v_exp_f32_e32 v124, v214
	v_pk_add_f32 v[102:103], v[114:115], v[102:103]
	v_exp_f32_e32 v126, v215
	v_sub_f32_e32 v95, v95, v117
	v_pk_add_f32 v[102:103], v[118:119], v[102:103]
	v_pk_mul_f32 v[52:53], v[52:53], v[128:129] op_sel_hi:[1,0]
	v_pk_mul_f32 v[50:51], v[50:51], v[128:129] op_sel_hi:[1,0]
	v_pk_mul_f32 v[56:57], v[56:57], v[128:129] op_sel_hi:[1,0]
	v_pk_mul_f32 v[54:55], v[54:55], v[128:129] op_sel_hi:[1,0]
	v_pk_mul_f32 v[60:61], v[60:61], v[128:129] op_sel_hi:[1,0]
	v_pk_mul_f32 v[58:59], v[58:59], v[128:129] op_sel_hi:[1,0]
	v_pk_mul_f32 v[64:65], v[64:65], v[128:129] op_sel_hi:[1,0]
	v_pk_mul_f32 v[62:63], v[62:63], v[128:129] op_sel_hi:[1,0]
	v_exp_f32_e32 v129, v95
	v_pk_add_f32 v[102:103], v[120:121], v[102:103]
	v_cvt_pk_bf16_f32 v82, v110, v112
	v_pk_add_f32 v[102:103], v[122:123], v[102:103]
	v_cvt_pk_bf16_f32 v83, v114, v118
	v_pk_add_f32 v[102:103], v[124:125], v[102:103]
	v_cvt_pk_bf16_f32 v84, v120, v122
	v_pk_add_f32 v[102:103], v[126:127], v[102:103]
	v_cvt_pk_bf16_f32 v85, v124, v126
	v_pk_fma_f32 v[88:89], v[88:89], v[128:129], v[102:103]
	v_mov_b32_e32 v102, v129
	v_pk_mul_f32 v[36:37], v[36:37], v[102:103] op_sel_hi:[1,0]
	v_pk_mul_f32 v[34:35], v[34:35], v[102:103] op_sel_hi:[1,0]
	v_pk_mul_f32 v[40:41], v[40:41], v[102:103] op_sel_hi:[1,0]
	v_pk_mul_f32 v[38:39], v[38:39], v[102:103] op_sel_hi:[1,0]
	v_pk_mul_f32 v[44:45], v[44:45], v[102:103] op_sel_hi:[1,0]
	v_pk_mul_f32 v[42:43], v[42:43], v[102:103] op_sel_hi:[1,0]
	v_pk_mul_f32 v[48:49], v[48:49], v[102:103] op_sel_hi:[1,0]
	v_pk_mul_f32 v[46:47], v[46:47], v[102:103] op_sel_hi:[1,0]
	v_cvt_pk_bf16_f32 v102, v111, v113
	v_cvt_pk_bf16_f32 v103, v115, v119
	v_cvt_pk_bf16_f32 v104, v121, v123
	v_cvt_pk_bf16_f32 v105, v125, v127
	s_setprio 1
	s_waitcnt lgkmcnt(6)
	v_mfma_f32_16x16x32_bf16 v[50:53], v[78:81], v[82:85], v[50:53]
	s_waitcnt lgkmcnt(4)
	v_mfma_f32_16x16x32_bf16 v[54:57], v[74:77], v[82:85], v[54:57]
	s_waitcnt lgkmcnt(2)
	v_mfma_f32_16x16x32_bf16 v[58:61], v[70:73], v[82:85], v[58:61]
	s_waitcnt lgkmcnt(0)
	v_mfma_f32_16x16x32_bf16 v[62:65], v[66:69], v[82:85], v[62:65]
	v_mfma_f32_16x16x32_bf16 v[34:37], v[78:81], v[102:105], v[34:37]
	v_mfma_f32_16x16x32_bf16 v[38:41], v[74:77], v[102:105], v[38:41]
	v_mfma_f32_16x16x32_bf16 v[42:45], v[70:73], v[102:105], v[42:45]
	v_mfma_f32_16x16x32_bf16 v[46:49], v[66:69], v[102:105], v[46:49]
	s_setprio 0
	v_mov_b32_e32 v82, v101
	v_mov_b32_e32 v95, v117
